# P0 adaLN GEMV: all 32 weight loads of a wave issued before the first wait (on top of the flattened transposes)
# baseline (speedup 1.0000x reference)
; #define LAS __attribute__((address_space(3)))
; template <int LO, int HI> __global__ void __launch_bounds__(NWAVES * 64, 2) fox_fwd(Args args) {
;     ...
; #pragma unroll 8
;             for (int kk = 0; kk < 32; ++kk) { const int k = wave * 128 + 4 * kk + kpar; const float wv = w_ada[(size_t)k * 3072 + col];
;                 const f32x4 c0 = *(const LAS f32x4*)(ct + k * 8), c1 = *(const LAS f32x4*)(ct + k * 8 + 4);
;                 acc[0] += c0[0] * wv; acc[1] += c0[1] * wv; acc[2] += c0[2] * wv; acc[3] += c0[3] * wv; acc[4] += c1[0] * wv; acc[5] += c1[1] * wv; acc[6] += c1[2] * wv; acc[7] += c1[3] * wv; }
.LBB0_20:
	v_mad_i64_i32 v[18:19], s[14:15], v3, s5, v[14:15]
	global_load_dword v100, v[18:19], off
	v_add_u32_e32 v26, 4, v3
	v_mad_i64_i32 v[20:21], s[14:15], v26, s5, v[14:15]
	global_load_dword v102, v[20:21], off
	v_add_u32_e32 v26, 8, v3
	v_mad_i64_i32 v[22:23], s[14:15], v26, s5, v[14:15]
	global_load_dword v104, v[22:23], off
	v_add_u32_e32 v26, 12, v3
	v_mad_i64_i32 v[24:25], s[14:15], v26, s5, v[14:15]
	global_load_dword v106, v[24:25], off
	v_add_u32_e32 v26, 16, v3
	v_mad_i64_i32 v[18:19], s[14:15], v26, s5, v[14:15]
	global_load_dword v108, v[18:19], off
	v_add_u32_e32 v26, 20, v3
	v_mad_i64_i32 v[20:21], s[14:15], v26, s5, v[14:15]
	global_load_dword v110, v[20:21], off
	v_add_u32_e32 v26, 24, v3
	v_mad_i64_i32 v[22:23], s[14:15], v26, s5, v[14:15]
	global_load_dword v112, v[22:23], off
	v_add_u32_e32 v26, 28, v3
	v_mad_i64_i32 v[24:25], s[14:15], v26, s5, v[14:15]
	global_load_dword v114, v[24:25], off
	v_add_u32_e32 v26, 32, v3
	v_mad_i64_i32 v[18:19], s[14:15], v26, s5, v[14:15]
	global_load_dword v116, v[18:19], off
	v_add_u32_e32 v26, 36, v3
	v_mad_i64_i32 v[20:21], s[14:15], v26, s5, v[14:15]
	global_load_dword v118, v[20:21], off
	v_add_u32_e32 v26, 40, v3
	v_mad_i64_i32 v[22:23], s[14:15], v26, s5, v[14:15]
	global_load_dword v120, v[22:23], off
	v_add_u32_e32 v26, 44, v3
	v_mad_i64_i32 v[24:25], s[14:15], v26, s5, v[14:15]
	global_load_dword v122, v[24:25], off
	v_add_u32_e32 v26, 48, v3
	v_mad_i64_i32 v[18:19], s[14:15], v26, s5, v[14:15]
	global_load_dword v124, v[18:19], off
	v_add_u32_e32 v26, 52, v3
	v_mad_i64_i32 v[20:21], s[14:15], v26, s5, v[14:15]
	global_load_dword v126, v[20:21], off
	v_add_u32_e32 v26, 56, v3
	v_mad_i64_i32 v[22:23], s[14:15], v26, s5, v[14:15]
	global_load_dword v128, v[22:23], off
	v_add_u32_e32 v26, 60, v3
	v_mad_i64_i32 v[24:25], s[14:15], v26, s5, v[14:15]
	global_load_dword v130, v[24:25], off
	v_add_u32_e32 v26, 64, v3
	v_mad_i64_i32 v[18:19], s[14:15], v26, s5, v[14:15]
	global_load_dword v132, v[18:19], off
	v_add_u32_e32 v26, 68, v3
	v_mad_i64_i32 v[20:21], s[14:15], v26, s5, v[14:15]
	global_load_dword v134, v[20:21], off
	v_add_u32_e32 v26, 72, v3
	v_mad_i64_i32 v[22:23], s[14:15], v26, s5, v[14:15]
	global_load_dword v136, v[22:23], off
	v_add_u32_e32 v26, 76, v3
	v_mad_i64_i32 v[24:25], s[14:15], v26, s5, v[14:15]
	global_load_dword v138, v[24:25], off
	v_add_u32_e32 v26, 80, v3
	v_mad_i64_i32 v[18:19], s[14:15], v26, s5, v[14:15]
	global_load_dword v140, v[18:19], off
	v_add_u32_e32 v26, 84, v3
	v_mad_i64_i32 v[20:21], s[14:15], v26, s5, v[14:15]
	global_load_dword v142, v[20:21], off
	v_add_u32_e32 v26, 88, v3
	v_mad_i64_i32 v[22:23], s[14:15], v26, s5, v[14:15]
	global_load_dword v144, v[22:23], off
	v_add_u32_e32 v26, 92, v3
	v_mad_i64_i32 v[24:25], s[14:15], v26, s5, v[14:15]
	global_load_dword v146, v[24:25], off
	v_add_u32_e32 v26, 96, v3
	v_mad_i64_i32 v[18:19], s[14:15], v26, s5, v[14:15]
	global_load_dword v148, v[18:19], off
	v_add_u32_e32 v26, 100, v3
	v_mad_i64_i32 v[20:21], s[14:15], v26, s5, v[14:15]
	global_load_dword v150, v[20:21], off
	v_add_u32_e32 v26, 104, v3
	v_mad_i64_i32 v[22:23], s[14:15], v26, s5, v[14:15]
	global_load_dword v152, v[22:23], off
	v_add_u32_e32 v26, 108, v3
	v_mad_i64_i32 v[24:25], s[14:15], v26, s5, v[14:15]
	global_load_dword v154, v[24:25], off
	v_add_u32_e32 v26, 112, v3
	v_mad_i64_i32 v[18:19], s[14:15], v26, s5, v[14:15]
	global_load_dword v156, v[18:19], off
	v_add_u32_e32 v26, 116, v3
	v_mad_i64_i32 v[20:21], s[14:15], v26, s5, v[14:15]
	global_load_dword v158, v[20:21], off
	v_add_u32_e32 v26, 120, v3
	v_mad_i64_i32 v[22:23], s[14:15], v26, s5, v[14:15]
	global_load_dword v160, v[22:23], off
	v_add_u32_e32 v26, 124, v3
	v_mad_i64_i32 v[24:25], s[14:15], v26, s5, v[14:15]
	global_load_dword v162, v[24:25], off
	ds_read_b128 v[18:21], v17
	ds_read_b128 v[22:25], v17 offset:16
	ds_read_b128 v[26:29], v17 offset:128
	ds_read_b128 v[30:33], v17 offset:144
	ds_read_b128 v[34:37], v17 offset:256
	ds_read_b128 v[38:41], v17 offset:272
	ds_read_b128 v[42:45], v17 offset:384
	ds_read_b128 v[46:49], v17 offset:400
	ds_read_b128 v[50:53], v17 offset:512
	ds_read_b128 v[54:57], v17 offset:528
	ds_read_b128 v[58:61], v17 offset:640
	ds_read_b128 v[62:65], v17 offset:656
	ds_read_b128 v[66:69], v17 offset:768
	ds_read_b128 v[70:73], v17 offset:784
	ds_read_b128 v[74:77], v17 offset:896
	ds_read_b128 v[78:81], v17 offset:912
	v_add_u32_e32 v17, 0x400, v17
	s_waitcnt vmcnt(31) lgkmcnt(14)
	v_pk_fma_f32 v[12:13], v[100:101], v[18:19], v[12:13] op_sel_hi:[0,1,1]
	v_pk_fma_f32 v[10:11], v[100:101], v[20:21], v[10:11] op_sel_hi:[0,1,1]
	v_pk_fma_f32 v[8:9], v[100:101], v[22:23], v[8:9] op_sel_hi:[0,1,1]
	v_pk_fma_f32 v[6:7], v[100:101], v[24:25], v[6:7] op_sel_hi:[0,1,1]
	s_waitcnt vmcnt(30) lgkmcnt(13)
	v_pk_fma_f32 v[12:13], v[102:103], v[26:27], v[12:13] op_sel_hi:[0,1,1]
	v_pk_fma_f32 v[10:11], v[102:103], v[28:29], v[10:11] op_sel_hi:[0,1,1]
	s_waitcnt lgkmcnt(12)
	v_pk_fma_f32 v[8:9], v[102:103], v[30:31], v[8:9] op_sel_hi:[0,1,1]
	v_pk_fma_f32 v[6:7], v[102:103], v[32:33], v[6:7] op_sel_hi:[0,1,1]
	s_waitcnt vmcnt(29) lgkmcnt(11)
	v_pk_fma_f32 v[12:13], v[104:105], v[34:35], v[12:13] op_sel_hi:[0,1,1]
	v_pk_fma_f32 v[10:11], v[104:105], v[36:37], v[10:11] op_sel_hi:[0,1,1]
	s_waitcnt lgkmcnt(10)
	v_pk_fma_f32 v[8:9], v[104:105], v[38:39], v[8:9] op_sel_hi:[0,1,1]
	v_pk_fma_f32 v[6:7], v[104:105], v[40:41], v[6:7] op_sel_hi:[0,1,1]
	s_waitcnt vmcnt(28) lgkmcnt(9)
	v_pk_fma_f32 v[12:13], v[106:107], v[42:43], v[12:13] op_sel_hi:[0,1,1]
	v_pk_fma_f32 v[10:11], v[106:107], v[44:45], v[10:11] op_sel_hi:[0,1,1]
	s_waitcnt lgkmcnt(8)
; #define LAS __attribute__((address_space(3)))
; template <int LO, int HI> __global__ void __launch_bounds__(NWAVES * 64, 2) fox_fwd(Args args) {
;     ...
;             for (int kk = 0; kk < 32; ++kk) { const int k = wave * 128 + 4 * kk + kpar; const float wv = w_ada[(size_t)k * 3072 + col];
;                 const f32x4 c0 = *(const LAS f32x4*)(ct + k * 8), c1 = *(const LAS f32x4*)(ct + k * 8 + 4);
;                 acc[0] += c0[0] * wv; acc[1] += c0[1] * wv; acc[2] += c0[2] * wv; acc[3] += c0[3] * wv; acc[4] += c1[0] * wv; acc[5] += c1[1] * wv; acc[6] += c1[2] * wv; acc[7] += c1[3] * wv; }
	v_pk_fma_f32 v[8:9], v[106:107], v[46:47], v[8:9] op_sel_hi:[0,1,1]
	v_pk_fma_f32 v[6:7], v[106:107], v[48:49], v[6:7] op_sel_hi:[0,1,1]
	s_waitcnt vmcnt(27) lgkmcnt(7)
	v_pk_fma_f32 v[12:13], v[108:109], v[50:51], v[12:13] op_sel_hi:[0,1,1]
	v_pk_fma_f32 v[10:11], v[108:109], v[52:53], v[10:11] op_sel_hi:[0,1,1]
	s_waitcnt lgkmcnt(6)
	v_pk_fma_f32 v[8:9], v[108:109], v[54:55], v[8:9] op_sel_hi:[0,1,1]
	v_pk_fma_f32 v[6:7], v[108:109], v[56:57], v[6:7] op_sel_hi:[0,1,1]
	s_waitcnt vmcnt(26) lgkmcnt(5)
	v_pk_fma_f32 v[12:13], v[110:111], v[58:59], v[12:13] op_sel_hi:[0,1,1]
	v_pk_fma_f32 v[10:11], v[110:111], v[60:61], v[10:11] op_sel_hi:[0,1,1]
	s_waitcnt lgkmcnt(4)
	v_pk_fma_f32 v[8:9], v[110:111], v[62:63], v[8:9] op_sel_hi:[0,1,1]
	v_pk_fma_f32 v[6:7], v[110:111], v[64:65], v[6:7] op_sel_hi:[0,1,1]
	s_waitcnt vmcnt(25) lgkmcnt(3)
	v_pk_fma_f32 v[12:13], v[112:113], v[66:67], v[12:13] op_sel_hi:[0,1,1]
	v_pk_fma_f32 v[10:11], v[112:113], v[68:69], v[10:11] op_sel_hi:[0,1,1]
	s_waitcnt lgkmcnt(2)
	v_pk_fma_f32 v[8:9], v[112:113], v[70:71], v[8:9] op_sel_hi:[0,1,1]
	v_pk_fma_f32 v[6:7], v[112:113], v[72:73], v[6:7] op_sel_hi:[0,1,1]
	s_waitcnt vmcnt(24) lgkmcnt(1)
	v_pk_fma_f32 v[12:13], v[114:115], v[74:75], v[12:13] op_sel_hi:[0,1,1]
	v_pk_fma_f32 v[10:11], v[114:115], v[76:77], v[10:11] op_sel_hi:[0,1,1]
	s_waitcnt lgkmcnt(0)
	v_pk_fma_f32 v[8:9], v[114:115], v[78:79], v[8:9] op_sel_hi:[0,1,1]
	v_pk_fma_f32 v[6:7], v[114:115], v[80:81], v[6:7] op_sel_hi:[0,1,1]
	ds_read_b128 v[18:21], v17
	ds_read_b128 v[22:25], v17 offset:16
	ds_read_b128 v[26:29], v17 offset:128
	ds_read_b128 v[30:33], v17 offset:144
	ds_read_b128 v[34:37], v17 offset:256
	ds_read_b128 v[38:41], v17 offset:272
	ds_read_b128 v[42:45], v17 offset:384
	ds_read_b128 v[46:49], v17 offset:400
	ds_read_b128 v[50:53], v17 offset:512
	ds_read_b128 v[54:57], v17 offset:528
	ds_read_b128 v[58:61], v17 offset:640
	ds_read_b128 v[62:65], v17 offset:656
	ds_read_b128 v[66:69], v17 offset:768
	ds_read_b128 v[70:73], v17 offset:784
	ds_read_b128 v[74:77], v17 offset:896
	ds_read_b128 v[78:81], v17 offset:912
	v_add_u32_e32 v17, 0x400, v17
	s_waitcnt vmcnt(23) lgkmcnt(14)
	v_pk_fma_f32 v[12:13], v[116:117], v[18:19], v[12:13] op_sel_hi:[0,1,1]
	v_pk_fma_f32 v[10:11], v[116:117], v[20:21], v[10:11] op_sel_hi:[0,1,1]
	v_pk_fma_f32 v[8:9], v[116:117], v[22:23], v[8:9] op_sel_hi:[0,1,1]
	v_pk_fma_f32 v[6:7], v[116:117], v[24:25], v[6:7] op_sel_hi:[0,1,1]
	s_waitcnt vmcnt(22) lgkmcnt(13)
	v_pk_fma_f32 v[12:13], v[118:119], v[26:27], v[12:13] op_sel_hi:[0,1,1]
	v_pk_fma_f32 v[10:11], v[118:119], v[28:29], v[10:11] op_sel_hi:[0,1,1]
	s_waitcnt lgkmcnt(12)
	v_pk_fma_f32 v[8:9], v[118:119], v[30:31], v[8:9] op_sel_hi:[0,1,1]
	v_pk_fma_f32 v[6:7], v[118:119], v[32:33], v[6:7] op_sel_hi:[0,1,1]
	s_waitcnt vmcnt(21) lgkmcnt(11)
	v_pk_fma_f32 v[12:13], v[120:121], v[34:35], v[12:13] op_sel_hi:[0,1,1]
	v_pk_fma_f32 v[10:11], v[120:121], v[36:37], v[10:11] op_sel_hi:[0,1,1]
	s_waitcnt lgkmcnt(10)
	v_pk_fma_f32 v[8:9], v[120:121], v[38:39], v[8:9] op_sel_hi:[0,1,1]
	v_pk_fma_f32 v[6:7], v[120:121], v[40:41], v[6:7] op_sel_hi:[0,1,1]
	s_waitcnt vmcnt(20) lgkmcnt(9)
	v_pk_fma_f32 v[12:13], v[122:123], v[42:43], v[12:13] op_sel_hi:[0,1,1]
	v_pk_fma_f32 v[10:11], v[122:123], v[44:45], v[10:11] op_sel_hi:[0,1,1]
	s_waitcnt lgkmcnt(8)
	v_pk_fma_f32 v[8:9], v[122:123], v[46:47], v[8:9] op_sel_hi:[0,1,1]
	v_pk_fma_f32 v[6:7], v[122:123], v[48:49], v[6:7] op_sel_hi:[0,1,1]
	s_waitcnt vmcnt(19) lgkmcnt(7)
	v_pk_fma_f32 v[12:13], v[124:125], v[50:51], v[12:13] op_sel_hi:[0,1,1]
	v_pk_fma_f32 v[10:11], v[124:125], v[52:53], v[10:11] op_sel_hi:[0,1,1]
	s_waitcnt lgkmcnt(6)
	v_pk_fma_f32 v[8:9], v[124:125], v[54:55], v[8:9] op_sel_hi:[0,1,1]
	v_pk_fma_f32 v[6:7], v[124:125], v[56:57], v[6:7] op_sel_hi:[0,1,1]
	s_waitcnt vmcnt(18) lgkmcnt(5)
	v_pk_fma_f32 v[12:13], v[126:127], v[58:59], v[12:13] op_sel_hi:[0,1,1]
	v_pk_fma_f32 v[10:11], v[126:127], v[60:61], v[10:11] op_sel_hi:[0,1,1]
	s_waitcnt lgkmcnt(4)
	v_pk_fma_f32 v[8:9], v[126:127], v[62:63], v[8:9] op_sel_hi:[0,1,1]
	v_pk_fma_f32 v[6:7], v[126:127], v[64:65], v[6:7] op_sel_hi:[0,1,1]
	s_waitcnt vmcnt(17) lgkmcnt(3)
	v_pk_fma_f32 v[12:13], v[128:129], v[66:67], v[12:13] op_sel_hi:[0,1,1]
	v_pk_fma_f32 v[10:11], v[128:129], v[68:69], v[10:11] op_sel_hi:[0,1,1]
	s_waitcnt lgkmcnt(2)
	v_pk_fma_f32 v[8:9], v[128:129], v[70:71], v[8:9] op_sel_hi:[0,1,1]
	v_pk_fma_f32 v[6:7], v[128:129], v[72:73], v[6:7] op_sel_hi:[0,1,1]
	s_waitcnt vmcnt(16) lgkmcnt(1)
	v_pk_fma_f32 v[12:13], v[130:131], v[74:75], v[12:13] op_sel_hi:[0,1,1]
	v_pk_fma_f32 v[10:11], v[130:131], v[76:77], v[10:11] op_sel_hi:[0,1,1]
	s_waitcnt lgkmcnt(0)
	v_pk_fma_f32 v[8:9], v[130:131], v[78:79], v[8:9] op_sel_hi:[0,1,1]
	v_pk_fma_f32 v[6:7], v[130:131], v[80:81], v[6:7] op_sel_hi:[0,1,1]
	ds_read_b128 v[18:21], v17
	ds_read_b128 v[22:25], v17 offset:16
	ds_read_b128 v[26:29], v17 offset:128
	ds_read_b128 v[30:33], v17 offset:144
	ds_read_b128 v[34:37], v17 offset:256
	ds_read_b128 v[38:41], v17 offset:272
	ds_read_b128 v[42:45], v17 offset:384
	ds_read_b128 v[46:49], v17 offset:400
	ds_read_b128 v[50:53], v17 offset:512
	ds_read_b128 v[54:57], v17 offset:528
	ds_read_b128 v[58:61], v17 offset:640
	ds_read_b128 v[62:65], v17 offset:656
	ds_read_b128 v[66:69], v17 offset:768
	ds_read_b128 v[70:73], v17 offset:784
	ds_read_b128 v[74:77], v17 offset:896
	ds_read_b128 v[78:81], v17 offset:912
	v_add_u32_e32 v17, 0x400, v17
	s_waitcnt vmcnt(15) lgkmcnt(14)
; #define LAS __attribute__((address_space(3)))
; template <int LO, int HI> __global__ void __launch_bounds__(NWAVES * 64, 2) fox_fwd(Args args) {
;     ...
;             for (int kk = 0; kk < 32; ++kk) { const int k = wave * 128 + 4 * kk + kpar; const float wv = w_ada[(size_t)k * 3072 + col];
;                 const f32x4 c0 = *(const LAS f32x4*)(ct + k * 8), c1 = *(const LAS f32x4*)(ct + k * 8 + 4);
;                 acc[0] += c0[0] * wv; acc[1] += c0[1] * wv; acc[2] += c0[2] * wv; acc[3] += c0[3] * wv; acc[4] += c1[0] * wv; acc[5] += c1[1] * wv; acc[6] += c1[2] * wv; acc[7] += c1[3] * wv; }
; #pragma unroll
;             for (int b = 0; b < 8; ++b) { acc[b] += __shfl_xor(acc[b], 16); acc[b] += __shfl_xor(acc[b], 32); if (lane < 16) red[(wave * 8 + b) * 16 + lane] = acc[b]; }
	v_pk_fma_f32 v[12:13], v[132:133], v[18:19], v[12:13] op_sel_hi:[0,1,1]
	v_pk_fma_f32 v[10:11], v[132:133], v[20:21], v[10:11] op_sel_hi:[0,1,1]
	v_pk_fma_f32 v[8:9], v[132:133], v[22:23], v[8:9] op_sel_hi:[0,1,1]
	v_pk_fma_f32 v[6:7], v[132:133], v[24:25], v[6:7] op_sel_hi:[0,1,1]
	s_waitcnt vmcnt(14) lgkmcnt(13)
	v_pk_fma_f32 v[12:13], v[134:135], v[26:27], v[12:13] op_sel_hi:[0,1,1]
	v_pk_fma_f32 v[10:11], v[134:135], v[28:29], v[10:11] op_sel_hi:[0,1,1]
	s_waitcnt lgkmcnt(12)
	v_pk_fma_f32 v[8:9], v[134:135], v[30:31], v[8:9] op_sel_hi:[0,1,1]
	v_pk_fma_f32 v[6:7], v[134:135], v[32:33], v[6:7] op_sel_hi:[0,1,1]
	s_waitcnt vmcnt(13) lgkmcnt(11)
	v_pk_fma_f32 v[12:13], v[136:137], v[34:35], v[12:13] op_sel_hi:[0,1,1]
	v_pk_fma_f32 v[10:11], v[136:137], v[36:37], v[10:11] op_sel_hi:[0,1,1]
	s_waitcnt lgkmcnt(10)
	v_pk_fma_f32 v[8:9], v[136:137], v[38:39], v[8:9] op_sel_hi:[0,1,1]
	v_pk_fma_f32 v[6:7], v[136:137], v[40:41], v[6:7] op_sel_hi:[0,1,1]
	s_waitcnt vmcnt(12) lgkmcnt(9)
	v_pk_fma_f32 v[12:13], v[138:139], v[42:43], v[12:13] op_sel_hi:[0,1,1]
	v_pk_fma_f32 v[10:11], v[138:139], v[44:45], v[10:11] op_sel_hi:[0,1,1]
	s_waitcnt lgkmcnt(8)
	v_pk_fma_f32 v[8:9], v[138:139], v[46:47], v[8:9] op_sel_hi:[0,1,1]
	v_pk_fma_f32 v[6:7], v[138:139], v[48:49], v[6:7] op_sel_hi:[0,1,1]
	s_waitcnt vmcnt(11) lgkmcnt(7)
	v_pk_fma_f32 v[12:13], v[140:141], v[50:51], v[12:13] op_sel_hi:[0,1,1]
	v_pk_fma_f32 v[10:11], v[140:141], v[52:53], v[10:11] op_sel_hi:[0,1,1]
	s_waitcnt lgkmcnt(6)
	v_pk_fma_f32 v[8:9], v[140:141], v[54:55], v[8:9] op_sel_hi:[0,1,1]
	v_pk_fma_f32 v[6:7], v[140:141], v[56:57], v[6:7] op_sel_hi:[0,1,1]
	s_waitcnt vmcnt(10) lgkmcnt(5)
	v_pk_fma_f32 v[12:13], v[142:143], v[58:59], v[12:13] op_sel_hi:[0,1,1]
	v_pk_fma_f32 v[10:11], v[142:143], v[60:61], v[10:11] op_sel_hi:[0,1,1]
	s_waitcnt lgkmcnt(4)
	v_pk_fma_f32 v[8:9], v[142:143], v[62:63], v[8:9] op_sel_hi:[0,1,1]
	v_pk_fma_f32 v[6:7], v[142:143], v[64:65], v[6:7] op_sel_hi:[0,1,1]
	s_waitcnt vmcnt(9) lgkmcnt(3)
	v_pk_fma_f32 v[12:13], v[144:145], v[66:67], v[12:13] op_sel_hi:[0,1,1]
	v_pk_fma_f32 v[10:11], v[144:145], v[68:69], v[10:11] op_sel_hi:[0,1,1]
	s_waitcnt lgkmcnt(2)
	v_pk_fma_f32 v[8:9], v[144:145], v[70:71], v[8:9] op_sel_hi:[0,1,1]
	v_pk_fma_f32 v[6:7], v[144:145], v[72:73], v[6:7] op_sel_hi:[0,1,1]
	s_waitcnt vmcnt(8) lgkmcnt(1)
	v_pk_fma_f32 v[12:13], v[146:147], v[74:75], v[12:13] op_sel_hi:[0,1,1]
	v_pk_fma_f32 v[10:11], v[146:147], v[76:77], v[10:11] op_sel_hi:[0,1,1]
	s_waitcnt lgkmcnt(0)
	v_pk_fma_f32 v[8:9], v[146:147], v[78:79], v[8:9] op_sel_hi:[0,1,1]
	v_pk_fma_f32 v[6:7], v[146:147], v[80:81], v[6:7] op_sel_hi:[0,1,1]
	ds_read_b128 v[18:21], v17
	ds_read_b128 v[22:25], v17 offset:16
	ds_read_b128 v[26:29], v17 offset:128
	ds_read_b128 v[30:33], v17 offset:144
	ds_read_b128 v[34:37], v17 offset:256
	ds_read_b128 v[38:41], v17 offset:272
	ds_read_b128 v[42:45], v17 offset:384
	ds_read_b128 v[46:49], v17 offset:400
	ds_read_b128 v[50:53], v17 offset:512
	ds_read_b128 v[54:57], v17 offset:528
	ds_read_b128 v[58:61], v17 offset:640
	ds_read_b128 v[62:65], v17 offset:656
	ds_read_b128 v[66:69], v17 offset:768
	ds_read_b128 v[70:73], v17 offset:784
	ds_read_b128 v[74:77], v17 offset:896
	ds_read_b128 v[78:81], v17 offset:912
	v_add_u32_e32 v17, 0x400, v17
	s_waitcnt vmcnt(7) lgkmcnt(14)
	v_pk_fma_f32 v[12:13], v[148:149], v[18:19], v[12:13] op_sel_hi:[0,1,1]
	v_pk_fma_f32 v[10:11], v[148:149], v[20:21], v[10:11] op_sel_hi:[0,1,1]
	v_pk_fma_f32 v[8:9], v[148:149], v[22:23], v[8:9] op_sel_hi:[0,1,1]
	v_pk_fma_f32 v[6:7], v[148:149], v[24:25], v[6:7] op_sel_hi:[0,1,1]
	s_waitcnt vmcnt(6) lgkmcnt(13)
	v_pk_fma_f32 v[12:13], v[150:151], v[26:27], v[12:13] op_sel_hi:[0,1,1]
	v_pk_fma_f32 v[10:11], v[150:151], v[28:29], v[10:11] op_sel_hi:[0,1,1]
	s_waitcnt lgkmcnt(12)
	v_pk_fma_f32 v[8:9], v[150:151], v[30:31], v[8:9] op_sel_hi:[0,1,1]
	v_pk_fma_f32 v[6:7], v[150:151], v[32:33], v[6:7] op_sel_hi:[0,1,1]
	s_waitcnt vmcnt(5) lgkmcnt(11)
	v_pk_fma_f32 v[12:13], v[152:153], v[34:35], v[12:13] op_sel_hi:[0,1,1]
	v_pk_fma_f32 v[10:11], v[152:153], v[36:37], v[10:11] op_sel_hi:[0,1,1]
	s_waitcnt lgkmcnt(10)
	v_pk_fma_f32 v[8:9], v[152:153], v[38:39], v[8:9] op_sel_hi:[0,1,1]
	v_pk_fma_f32 v[6:7], v[152:153], v[40:41], v[6:7] op_sel_hi:[0,1,1]
	s_waitcnt vmcnt(4) lgkmcnt(9)
	v_pk_fma_f32 v[12:13], v[154:155], v[42:43], v[12:13] op_sel_hi:[0,1,1]
	v_pk_fma_f32 v[10:11], v[154:155], v[44:45], v[10:11] op_sel_hi:[0,1,1]
	s_waitcnt lgkmcnt(8)
	v_pk_fma_f32 v[8:9], v[154:155], v[46:47], v[8:9] op_sel_hi:[0,1,1]
	v_pk_fma_f32 v[6:7], v[154:155], v[48:49], v[6:7] op_sel_hi:[0,1,1]
	s_waitcnt vmcnt(3) lgkmcnt(7)
	v_pk_fma_f32 v[12:13], v[156:157], v[50:51], v[12:13] op_sel_hi:[0,1,1]
	v_pk_fma_f32 v[10:11], v[156:157], v[52:53], v[10:11] op_sel_hi:[0,1,1]
	s_waitcnt lgkmcnt(6)
	v_pk_fma_f32 v[8:9], v[156:157], v[54:55], v[8:9] op_sel_hi:[0,1,1]
	v_pk_fma_f32 v[6:7], v[156:157], v[56:57], v[6:7] op_sel_hi:[0,1,1]
	s_waitcnt vmcnt(2) lgkmcnt(5)
	v_pk_fma_f32 v[12:13], v[158:159], v[58:59], v[12:13] op_sel_hi:[0,1,1]
	v_pk_fma_f32 v[10:11], v[158:159], v[60:61], v[10:11] op_sel_hi:[0,1,1]
	s_waitcnt lgkmcnt(4)
	v_pk_fma_f32 v[8:9], v[158:159], v[62:63], v[8:9] op_sel_hi:[0,1,1]
	v_pk_fma_f32 v[6:7], v[158:159], v[64:65], v[6:7] op_sel_hi:[0,1,1]
	s_waitcnt vmcnt(1) lgkmcnt(3)
	v_pk_fma_f32 v[12:13], v[160:161], v[66:67], v[12:13] op_sel_hi:[0,1,1]
	v_pk_fma_f32 v[10:11], v[160:161], v[68:69], v[10:11] op_sel_hi:[0,1,1]
	s_waitcnt lgkmcnt(2)
	v_pk_fma_f32 v[8:9], v[160:161], v[70:71], v[8:9] op_sel_hi:[0,1,1]
	v_pk_fma_f32 v[6:7], v[160:161], v[72:73], v[6:7] op_sel_hi:[0,1,1]
	s_waitcnt vmcnt(0) lgkmcnt(1)
	v_pk_fma_f32 v[12:13], v[162:163], v[74:75], v[12:13] op_sel_hi:[0,1,1]
	v_pk_fma_f32 v[10:11], v[162:163], v[76:77], v[10:11] op_sel_hi:[0,1,1]
	s_waitcnt lgkmcnt(0)
	v_pk_fma_f32 v[8:9], v[162:163], v[78:79], v[8:9] op_sel_hi:[0,1,1]
	v_pk_fma_f32 v[6:7], v[162:163], v[80:81], v[6:7] op_sel_hi:[0,1,1]
	v_mbcnt_lo_u32_b32 v3, -1, 0
	v_mbcnt_hi_u32_b32 v14, -1, v3
	v_and_b32_e32 v15, 64, v14
	v_xor_b32_e32 v3, 16, v14
	v_add_u32_e32 v15, 64, v15
	v_cmp_lt_i32_e32 vcc, v3, v15
	v_xor_b32_e32 v18, 32, v14
	s_lshl_b32 s4, s26, 9
	v_cndmask_b32_e32 v3, v14, v3, vcc
	v_lshlrev_b32_e32 v3, 2, v3
	ds_bpermute_b32 v17, v3, v12
	v_cmp_lt_i32_e32 vcc, v18, v15
	s_add_i32 s4, s4, 0
	s_waitcnt lgkmcnt(0)
	v_add_f32_e32 v15, v12, v17
	v_cndmask_b32_e32 v14, v14, v18, vcc
	v_lshlrev_b32_e32 v14, 2, v14
	ds_bpermute_b32 v17, v14, v15
	v_cmp_gt_u32_e32 vcc, 16, v16
	v_lshl_add_u32 v12, v16, 2, s4
	s_and_saveexec_b64 s[4:5], vcc
	s_cbranch_execz .LBB0_23
	s_waitcnt lgkmcnt(0)
	v_add_f32_e32 v15, v15, v17
	ds_write_b32 v12, v15 offset:32768
